# attention loop: bf16 conversion of P groups 1-3 moved into the PV MFMA shadows (on top of early V reads)
# baseline (speedup 1.0000x reference)
.LBB0_269:
	v_exp_f32_e32 v180, v82
	v_exp_f32_e32 v181, v66
	v_exp_f32_e32 v178, v83
	v_exp_f32_e32 v179, v67
	v_exp_f32_e32 v176, v84
	v_exp_f32_e32 v177, v68
	v_exp_f32_e32 v174, v85
	v_exp_f32_e32 v175, v69
	v_exp_f32_e32 v172, v86
	v_exp_f32_e32 v173, v70
	v_exp_f32_e32 v170, v87
	v_exp_f32_e32 v171, v71
	v_exp_f32_e32 v168, v88
	v_exp_f32_e32 v169, v72
	v_exp_f32_e32 v88, v89
	v_exp_f32_e32 v89, v73
	v_exp_f32_e32 v86, v90
	v_exp_f32_e32 v87, v74
	v_exp_f32_e32 v84, v91
	v_exp_f32_e32 v85, v75
	v_exp_f32_e32 v82, v92
	v_exp_f32_e32 v83, v76
	v_exp_f32_e32 v74, v93
	v_exp_f32_e32 v75, v77
	v_exp_f32_e32 v72, v94
	v_exp_f32_e32 v73, v78
	v_exp_f32_e32 v70, v95
	v_exp_f32_e32 v71, v79
	v_exp_f32_e32 v68, v96
	v_exp_f32_e32 v69, v80
	v_exp_f32_e32 v66, v97
	v_exp_f32_e32 v67, v81
	v_cvt_pk_bf16_f32 v76, v180, v178
	v_cvt_pk_bf16_f32 v77, v176, v174
	v_cvt_pk_bf16_f32 v78, v172, v170
	v_cvt_pk_bf16_f32 v79, v168, v88
	s_nop 1
	s_waitcnt lgkmcnt(3)
	v_mfma_f32_32x32x16_bf16 v[50:65], v[192:195], v[76:79], v[50:65]
	v_cvt_pk_bf16_f32 v90, v86, v84
	ds_read2_b64 v[192:195], v246 offset0:4 offset1:6
	s_add_i32 s5, s4, -1
	s_bitcmp1_b32 s5, 0
	s_cselect_b32 s5, 0x8c00, 0
	v_add_f32_e32 v238, v180, v181
	v_add_f32_e32 v239, v172, v173
	s_waitcnt lgkmcnt(3)
	v_mfma_f32_32x32x16_bf16 v[34:49], v[206:209], v[76:79], v[34:49]
	v_cvt_pk_bf16_f32 v91, v82, v74
	ds_read2_b64 v[206:209], v247 offset0:36 offset1:38
	v_lshlrev_b32_e32 v250, 1, v153
	v_add3_u32 v250, s5, v250, v152
	v_add_f32_e32 v240, v86, v87
	v_add_f32_e32 v241, v72, v73
	s_waitcnt lgkmcnt(3)
	v_mfma_f32_32x32x16_bf16 v[18:33], v[210:213], v[76:79], v[18:33]
	v_cvt_pk_bf16_f32 v92, v72, v70
	ds_read2_b64 v[210:213], v248 offset0:68 offset1:70
	s_waitcnt vmcnt(0)
	ds_write_b128 v250, v[114:117]
	v_add_f32_e32 v238, v238, v178
	v_add_f32_e32 v239, v239, v170
	s_waitcnt lgkmcnt(4)
	v_mfma_f32_32x32x16_bf16 v[2:17], v[222:225], v[76:79], v[2:17]
	v_cvt_pk_bf16_f32 v93, v68, v66
	ds_read2_b64 v[222:225], v249 offset0:100 offset1:102
	ds_write_b128 v250, v[118:121] offset:4608
	v_add_f32_e32 v240, v240, v84
	v_add_f32_e32 v241, v241, v70
	s_waitcnt lgkmcnt(5)
	v_mfma_f32_32x32x16_bf16 v[50:65], v[192:195], v[90:93], v[50:65]
	v_cvt_pk_bf16_f32 v94, v181, v179
	ds_read2_b64 v[192:195], v246 offset0:8 offset1:10
	ds_write_b128 v250, v[122:125] offset:9216
	v_add_f32_e32 v238, v238, v179
	v_add_f32_e32 v239, v239, v171
	s_waitcnt lgkmcnt(6)
	v_mfma_f32_32x32x16_bf16 v[34:49], v[206:209], v[90:93], v[34:49]
	v_cvt_pk_bf16_f32 v95, v177, v175
	ds_read2_b64 v[206:209], v247 offset0:40 offset1:42
	ds_write_b128 v250, v[126:129] offset:13824
	v_add_f32_e32 v240, v240, v85
	v_add_f32_e32 v241, v241, v71
	s_waitcnt lgkmcnt(7)
	v_mfma_f32_32x32x16_bf16 v[18:33], v[210:213], v[90:93], v[18:33]
	v_cvt_pk_bf16_f32 v96, v173, v171
	ds_read2_b64 v[210:213], v248 offset0:72 offset1:74
	v_lshlrev_b32_e32 v251, 1, v182
	v_add3_u32 v251, s5, v251, v152
	v_add_f32_e32 v238, v238, v176
	v_add_f32_e32 v239, v239, v168
	s_waitcnt lgkmcnt(6)
	v_mfma_f32_32x32x16_bf16 v[2:17], v[222:225], v[90:93], v[2:17]
	v_cvt_pk_bf16_f32 v97, v169, v89
	ds_read2_b64 v[222:225], v249 offset0:104 offset1:106
	v_add_u32_e32 v214, 0x4800, v251
	ds_write2_b64 v214, v[130:131], v[132:133] offset1:1
	v_add_f32_e32 v240, v240, v82
	v_add_f32_e32 v241, v241, v68
	s_waitcnt lgkmcnt(6)
	v_mfma_f32_32x32x16_bf16 v[50:65], v[192:195], v[94:97], v[50:65]
	v_cvt_pk_bf16_f32 v188, v87, v85
	ds_read2_b64 v[192:195], v246 offset0:12 offset1:14
	v_add_u32_e32 v214, 0x5900, v251
	ds_write2_b64 v214, v[134:135], v[136:137] offset1:1
	v_add_f32_e32 v238, v238, v177
	v_add_f32_e32 v239, v239, v169
	s_waitcnt lgkmcnt(6)
	v_mfma_f32_32x32x16_bf16 v[34:49], v[206:209], v[94:97], v[34:49]
	v_cvt_pk_bf16_f32 v189, v83, v75
	ds_read2_b64 v[206:209], v247 offset0:44 offset1:46
	v_add_u32_e32 v214, 0x6a00, v251
	ds_write2_b64 v214, v[138:139], v[140:141] offset1:1
	v_add_f32_e32 v240, v240, v83
	v_add_f32_e32 v241, v241, v69
	s_waitcnt lgkmcnt(6)
	v_mfma_f32_32x32x16_bf16 v[18:33], v[210:213], v[94:97], v[18:33]
	v_cvt_pk_bf16_f32 v190, v73, v71
	ds_read2_b64 v[210:213], v248 offset0:76 offset1:78
	v_add_u32_e32 v214, 0x7b00, v251
	ds_write2_b64 v214, v[142:143], v[144:145] offset1:1
	v_add_f32_e32 v238, v238, v174
	v_add_f32_e32 v239, v239, v88
	s_waitcnt lgkmcnt(7)
	v_mfma_f32_32x32x16_bf16 v[2:17], v[222:225], v[94:97], v[2:17]
	v_cvt_pk_bf16_f32 v191, v69, v67
	ds_read2_b64 v[222:225], v249 offset0:108 offset1:110
	global_load_dwordx4 v[114:117], v[156:157], off offset:-2048
	global_load_dwordx4 v[118:121], v[156:157], off offset:2048
	v_add_f32_e32 v240, v240, v74
	v_add_f32_e32 v241, v241, v66
	s_waitcnt lgkmcnt(6)
	v_mfma_f32_32x32x16_bf16 v[50:65], v[192:195], v[188:191], v[50:65]
	global_load_dwordx4 v[122:125], v[158:159], off offset:-2048
	global_load_dwordx4 v[126:129], v[158:159], off offset:2048
	v_add_f32_e32 v238, v238, v175
	v_add_f32_e32 v239, v239, v89
	s_waitcnt lgkmcnt(4)
	v_mfma_f32_32x32x16_bf16 v[34:49], v[206:209], v[188:191], v[34:49]
	global_load_dwordx4 v[130:133], v[160:161], off offset:384
	global_load_dwordx4 v[134:137], v[162:163], off offset:384
	v_add_f32_e32 v240, v240, v75
	v_add_f32_e32 v241, v241, v67
	s_waitcnt lgkmcnt(2)
	v_mfma_f32_32x32x16_bf16 v[18:33], v[210:213], v[188:191], v[18:33]
	global_load_dwordx4 v[138:141], v[164:165], off offset:384
	global_load_dwordx4 v[142:145], v[166:167], off offset:384
	v_add_f32_e32 v238, v238, v239
	v_add_f32_e32 v240, v240, v241
	s_waitcnt lgkmcnt(0)
	v_mfma_f32_32x32x16_bf16 v[2:17], v[222:225], v[188:191], v[2:17]
	v_add_f32_e32 v238, v238, v240
	s_nop 0
	s_branch .LBB0_266
